# v36 + code placement: three 4-byte pads restore the baseline byte phase (mod 8) of the compress/GLA/scan loops and the W_out/FFN1/FFN2 GEMM K-loops and LN loops
# baseline (speedup 1.0000x reference)
; #define LAS __attribute__((address_space(3)))
; #define CMP_LOADB(dst, ll_) do { _Pragma("unroll") for (int ks = 0; ks < 2; ++ks) _Pragma("unroll") for (int ct = 0; ct < 2; ++ct) dst[ks][ct] = *(const bf16x8*)(W1T + (size_t)(32 * w + 16 * ct + fr) * 2048 + (ll_) * 64 + ks * 32 + fq * 8); } while (0)
; DI void nsa_compress_item(KA a, const int l, LAS unsigned char* lds, const int it) {
;     ...
;     const int kv = it & 1, ctile = (it >> 1) & 1, bg = it >> 2, b = bg >> 1, g = bg & 1;
;     unsigned char* ws = a->ws; const bf16* H = (const bf16*)(ws + WS_H); const float* ctab = (const float*)(ws + WS_COS); const float* stab = (const float*)(ws + WS_SIN);
;     LAS bf16* At = (LAS bf16*)lds; LAS bf16* Hd = At + 64 * PA;
;     const bf16* W1T = (const bf16*)(ws + WS_WC1 + (size_t)(l * 2 + kv) * MiB);
;     const bf16* W2T = (const bf16*)(ws + WS_SMALL + l * SMALL_STRIDE + (kv ? SM_WV2T : SM_WK2T));
;     const float* pos = a->in[kv ? I_POSV : I_POSK] + l * 32 * 64;
;     const int colbase = (kv ? C_NVC : C_NKC) + g * 64;
;     f32x4 acc[4][2];
; #pragma unroll
;     for (int rt = 0; rt < 4; ++rt) { acc[rt][0] = ZERO4; acc[rt][1] = ZERO4; }
;     const bool stager = (tid & 7) < 4; const int sc_ = tid >> 3, sm_ = tid & 3, scg = 64 * ctile + sc_; const bool svalid = scg < 127;
;     v4u xr1 = {0u, 0u, 0u, 0u}, xr2 = {0u, 0u, 0u, 0u}; f32x4 cs[2], sn[2], ps1[2], ps2[2]; bf16x8 bcur[2][2], bnxt[2][2];
;     ...
;     CMP_LOADA(0); CMP_LOADB(bcur, 0);
.LBB0_469:
	s_and_b64 vcc, exec, s[0:1]
	s_cbranch_vccz .LBB0_322
	s_nop 0
	s_and_b32 s61, s60, 1
	v_mov_b32_e32 v118, v232
	s_lshl_b32 s0, s61, 3
	s_load_dwordx2 s[0:1], s[12:13], s0 offset:0xa8
	v_ashrrev_i32_e32 v97, 3, v118
	v_and_b32_e32 v0, 4, v118
	v_and_b32_e32 v33, 3, v118
	s_movk_i32 s42, 0x7e
	s_waitcnt lgkmcnt(0)
	s_add_u32 s54, s0, s52
	s_addc_u32 s55, s1, s53
	s_cmp_eq_u32 s61, 0
	s_cselect_b64 s[40:41], -1, 0
	s_and_b64 s[0:1], s[40:41], exec
	s_movk_i32 s0, 0xa30
	s_cselect_b32 s45, s0, 0xab0
	s_lshl_b32 s0, s60, 5
	s_and_b32 s33, s0, 64
	v_add_u32_e32 v32, s33, v97
	s_movk_i32 s0, 0x7f
	v_cmp_eq_u32_e64 s[2:3], 0, v0
	v_cmp_ne_u32_e64 s[4:5], 0, v0
	v_cmp_gt_i32_e64 s[0:1], s0, v32
	v_cmp_lt_i32_e32 vcc, s42, v32
	v_lshlrev_b32_e32 v192, 3, v33
	s_and_saveexec_b64 s[42:43], s[4:5]
	s_xor_b64 s[42:43], exec, s[42:43]
	v_lshlrev_b32_e32 v192, 3, v33
	s_or_saveexec_b64 s[56:57], s[42:43]
	s_ashr_i32 s42, s60, 2
	s_lshl_b32 s43, s42, 6
	v_mov_b32_e32 v2, v193
	v_mov_b32_e32 v3, v193
	s_and_b32 s43, s43, 64
	v_mov_b32_e32 v0, v193
	v_mov_b32_e32 v1, v193
	v_mov_b64_e32 v[6:7], v[2:3]
	s_ashr_i32 s44, s60, 3
	s_or_b32 s43, s45, s43
	v_mov_b64_e32 v[4:5], v[0:1]
	s_xor_b64 exec, exec, s[56:57]
	s_cbranch_execz .LBB0_479
	s_and_saveexec_b64 s[58:59], vcc
	s_xor_b64 s[58:59], exec, s[58:59]
	v_lshlrev_b32_e32 v192, 3, v33
	s_or_saveexec_b64 s[58:59], s[58:59]
	v_mov_b32_e32 v4, v193
	v_mov_b32_e32 v5, v193
	v_mov_b32_e32 v6, v193
	v_mov_b32_e32 v7, v193
	v_mov_b64_e32 v[0:1], v[4:5]
	v_mov_b64_e32 v[2:3], v[6:7]
	s_xor_b64 exec, exec, s[58:59]
	s_cbranch_execz .LBB0_478
	v_lshlrev_b32_e32 v0, 4, v32
	s_ashr_i32 s45, s44, 31
	s_lshl_b64 s[66:67], s[44:45], 11
	v_ashrrev_i32_e32 v1, 31, v0
	v_lshl_add_u64 v[0:1], s[66:67], 0, v[0:1]
	v_mov_b64_e32 v[2:3], s[16:17]
	s_movk_i32 s45, 0x1c00
	v_mad_u64_u32 v[2:3], s[66:67], v0, s45, v[2:3]
	v_mad_i32_i24 v3, v1, s45, v3
	s_lshl_b32 s90, s43, 1
	v_lshl_add_u64 v[0:1], v[2:3], 0, s[90:91]
	v_lshlrev_b32_e32 v2, 4, v33
	v_mov_b32_e32 v3, v193
	v_lshl_add_u64 v[4:5], v[0:1], 0, v[2:3]
	global_load_dwordx4 v[0:3], v[4:5], off
	s_nop 0
	global_load_dwordx4 v[4:7], v[4:5], off offset:64
	s_andn2_b64 vcc, exec, s[40:41]
	s_cbranch_vccnz .LBB0_478
	v_lshlrev_b32_e32 v8, 9, v32
	v_ashrrev_i32_e32 v9, 31, v8
	v_lshlrev_b64 v[8:9], 2, v[8:9]
	v_lshl_add_u64 v[10:11], s[18:19], 0, v[8:9]
	v_lshlrev_b32_e32 v12, 2, v192
	v_mov_b32_e32 v13, v193
	v_lshl_add_u64 v[8:9], s[20:21], 0, v[8:9]
	v_lshl_add_u64 v[14:15], v[10:11], 0, v[12:13]
	v_lshl_add_u64 v[20:21], v[8:9], 0, v[12:13]
	global_load_dwordx4 v[8:11], v[14:15], off offset:16
	global_load_dwordx4 v[16:19], v[14:15], off
	s_nop 0
	global_load_dwordx4 v[12:15], v[20:21], off offset:16
	s_nop 0
	global_load_dwordx4 v[20:23], v[20:21], off

; #define LAS __attribute__((address_space(3)))
; DI f32x16 mma32(bf16x8 a, bf16x8 b, f32x16 c) { return __builtin_amdgcn_mfma_f32_32x32x16_bf16(a, b, c, 0, 0, 0); }
; #define NSA_STORE(Kb, Vb) do { *(LAS v4u*)((Kb) + skey * PA + 8 * sch) = kreg; LAS unsigned* d0_ = (LAS unsigned*)((Vb) + (4 * sdg) * PV + vpos(2 * skp)); \
;         d0_[0] = (vr0.x & 0xffffu) | (vr1.x << 16); d0_[PV / 2] = (vr0.x >> 16) | (vr1.x & 0xffff0000u); d0_[PV] = (vr0.y & 0xffffu) | (vr1.y << 16); d0_[3 * PV / 2] = (vr0.y >> 16) | (vr1.y & 0xffff0000u); } while (0)
; DI void nsa_item(KA a, LAS unsigned char* lds, const int it) {
;     ...
;         of[0] = ot[0] * g0; of[1] = ot[1] * g0;
;         if (qb >= 16) {
;     ...
;     const unsigned mysel = SELM[tql]; const int n = *NLIST;
;     LAS bf16* Kt1 = (LAS bf16*)(lds + NSA_KT1); LAS bf16* VT1 = (LAS bf16*)(lds + NSA_VT1);
;     NSA_STORE(Kt, VT);
;     NSA_LOAD(LIST[1]);
;     __syncthreads();
;     float m_ref = 0.f, l_run = 0.f; f32x16 ot[2] = {ZERO16, ZERO16}; int curtype = 0;
;     for (int i = 0; i < n; ++i) {
;         const int desc = LIST[i]; const int ty = desc >> 8, j = desc & 255;
;         const LAS bf16* Kc = (i & 1) ? Kt1 : Kt; const LAS bf16* Vc = (i & 1) ? VT1 : VT;
;         if (ty != curtype) { const float lt = l_run + __shfl_xor(l_run, 32); const float sc = g1 / lt; of[0] += ot[0] * sc; of[1] += ot[1] * sc; ot[0] = ZERO16; ot[1] = ZERO16; m_ref = 0.f; l_run = 0.f; curtype = ty; }
;         const bool rowoff = (ty == 0) && (((mysel >> j) & 1u) == 0u);
;         const int mode = (j == qb) ? 1 : ((ty == 1 && j == qb - 8) ? 2 : 0);
;         const float init = rowoff ? -INFINITY : -m_ref;
;         f32x16 st[2];
; #pragma unroll
;         for (int i2 = 0; i2 < 16; ++i2) { st[0][i2] = init; st[1][i2] = init; }
; #pragma unroll
;         for (int kt = 0; kt < 2; ++kt)
; #pragma unroll
;             for (int s = 0; s < 4; ++s) { const bf16x8 af = *(const LAS bf16x8*)(Kc + (32 * kt + r) * PA + 16 * s + 8 * hf); st[kt] = mma32(af, bq[s], st[kt]); }
.LBB0_794:
	v_add_f32_e32 v33, 1.0, v33
	v_rcp_f32_e32 v34, v33
	s_andn2_b64 vcc, exec, s[0:1]
	v_readlane_b32 s90, v254, 47
	v_pk_mul_f32 v[124:125], v[34:35], v[30:31] op_sel_hi:[0,1]
	v_pk_mul_f32 v[120:121], v[34:35], v[28:29] op_sel_hi:[0,1]
	v_pk_mul_f32 v[116:117], v[34:35], v[26:27] op_sel_hi:[0,1]
	v_pk_mul_f32 v[112:113], v[34:35], v[24:25] op_sel_hi:[0,1]
	v_pk_mul_f32 v[108:109], v[34:35], v[22:23] op_sel_hi:[0,1]
	v_pk_mul_f32 v[104:105], v[34:35], v[20:21] op_sel_hi:[0,1]
	v_pk_mul_f32 v[100:101], v[34:35], v[18:19] op_sel_hi:[0,1]
	v_pk_mul_f32 v[96:97], v[34:35], v[16:17] op_sel_hi:[0,1]
	v_pk_mul_f32 v[122:123], v[34:35], v[14:15] op_sel_hi:[0,1]
	v_pk_mul_f32 v[118:119], v[34:35], v[12:13] op_sel_hi:[0,1]
	v_pk_mul_f32 v[114:115], v[34:35], v[10:11] op_sel_hi:[0,1]
	v_pk_mul_f32 v[110:111], v[34:35], v[8:9] op_sel_hi:[0,1]
	v_pk_mul_f32 v[106:107], v[34:35], v[6:7] op_sel_hi:[0,1]
	v_pk_mul_f32 v[102:103], v[34:35], v[4:5] op_sel_hi:[0,1]
	v_pk_mul_f32 v[98:99], v[34:35], v[2:3] op_sel_hi:[0,1]
	v_pk_mul_f32 v[94:95], v[34:35], v[0:1] op_sel_hi:[0,1]
	v_mov_b32_e32 v31, 0
	s_cbranch_vccnz .LBB0_811
	s_sub_i32 s85, 23, s40
	s_mov_b32 s87, 0
	s_mov_b32 s88, 0
	v_mov_b32_e32 v137, 0
	v_mov_b32_e32 v16, 0
	v_readlane_b32 s86, v254, 13
	v_mov_b32_e32 v135, 0
	v_mov_b32_e32 v0, 0
	v_mov_b32_e32 v1, v135
	v_mov_b32_e32 v2, v135
	v_mov_b32_e32 v3, v135
	v_mov_b32_e32 v4, v135
	v_mov_b32_e32 v5, v135
	v_mov_b32_e32 v6, v135
	v_mov_b32_e32 v7, v135
	v_mov_b32_e32 v8, v135
	v_mov_b32_e32 v9, v135
	v_mov_b32_e32 v10, v135
	v_mov_b32_e32 v11, v135
	v_mov_b32_e32 v12, v135
	v_mov_b32_e32 v13, v135
	v_mov_b32_e32 v14, v135
	v_mov_b32_e32 v15, v135
	v_mov_b32_e32 v17, v135
	v_mov_b32_e32 v18, v135
	v_mov_b32_e32 v19, v135
	v_mov_b32_e32 v20, v135
	v_mov_b32_e32 v21, v135
	v_mov_b32_e32 v22, v135
	v_mov_b32_e32 v23, v135
	v_mov_b32_e32 v24, v135
	v_mov_b32_e32 v25, v135
	v_mov_b32_e32 v26, v135
	v_mov_b32_e32 v27, v135
	v_mov_b32_e32 v28, v135
	v_mov_b32_e32 v29, v135
	v_mov_b32_e32 v30, v135
	v_mov_b32_e32 v31, v135
	s_movk_i32 s74, 0x1c00
	v_mad_u32_u24 v190, v132, s74, v192
	v_mad_u32_u24 v251, v133, s74, v88
	v_add_u32_e32 v251, 0x100, v251
	v_add_u32_e32 v241, 0x1c00, v251
	v_readlane_b32 s74, v254, 48
	v_readlane_b32 s98, v254, 39
	v_readlane_b32 s99, v254, 40
	s_mov_b32 s100, 0x5040100
	s_mul_i32 s74, s74, 0x1c00
	s_lshl_b32 s75, s33, 1
	s_add_u32 s74, s74, s75
	s_add_u32 s98, s98, s74
	s_addc_u32 s99, s99, 0
	s_mov_b32 s101, 0x7060302
	v_and_b32_e32 v242, 31, v238
	v_lshrrev_b32_e32 v243, 5, v238
	v_lshlrev_b32_e32 v243, 2, v243
	v_sub_u32_e32 v242, v242, v243
	v_bfe_u32 v243, v232, 6, 1
	v_lshl_add_u32 v242, v243, 5, v242
	s_nop 0
	v_add3_u32 v231, 0, v90, v130
	s_movk_i32 s74, 0x4800
	v_add3_u32 v230, s74, v90, v131
	ds_read_b128 v[170:173], v231 offset:64
	ds_read_b128 v[178:181], v231 offset:4608
	ds_read_b128 v[182:185], v231 offset:4640
	ds_read_b128 v[186:189], v231 offset:4672
	ds_read_b128 v[206:209], v231 offset:4704
	ds_read_b128 v[174:177], v231 offset:96
	s_add_i32 s74, s86, -8
	v_mov_b32_e32 v244, s74
	ds_read_b32 v191, v244
	ds_read_b32 v250, v244 offset:8
	ds_read_b128 v[210:213], v230
	ds_read_b128 v[218:221], v230 offset:8704
	ds_read_b128 v[222:225], v230 offset:8736
	ds_read_b128 v[214:217], v230 offset:32
	ds_read_b128 v[226:229], v230 offset:64
	ds_read_b128 v[152:155], v230 offset:8768
	ds_read_b128 v[246:249], v230 offset:96
	ds_read_b128 v[144:147], v231
	ds_read_b128 v[148:151], v231 offset:32

;     __host__ __device__ bool next(int i, Unit& u) const {
;         const long L = (long)i * G + c; if (L >= nwg) return false;
;         int wgid = (int)L; { const int q = nwg / NXCD, r = nwg % NXCD, xcd = wgid % NXCD, off = wgid / NXCD; wgid = (xcd < r ? xcd * (q + 1) : r * (q + 1) + (xcd - r) * q) + off; }
;         const int nig = wgm * nN, gid = wgid / nig, fm = gid * wgm, gsz = (nM - fm) < wgm ? (nM - fm) : wgm;
;         u.pm = fm + ((wgid % nig) % gsz); u.pn = (wgid % nig) / gsz; return true;
.LBB0_1044:
	s_nop 0
	s_add_i32 s34, s34, 1
	v_readlane_b32 s9, v252, 9
	s_mul_i32 s9, s34, s9
	s_mul_hi_u32 s11, s34, s76
	s_add_i32 s11, s11, s9
	s_mul_i32 s9, s34, s76
	s_add_u32 s12, s9, s74
	v_readlane_b32 s9, v252, 8
	s_addc_u32 s13, s11, s9
	v_cmp_gt_i64_e32 vcc, s[12:13], v[200:201]
	v_cmp_lt_i64_e64 s[42:43], s[12:13], v[198:199]
	s_cbranch_vccnz .LBB0_1050
	s_ashr_i32 s8, s12, 31
	s_lshr_b32 s8, s8, 29
	s_add_i32 s10, s12, s8
	s_and_b32 s8, s10, -8
	s_sub_i32 s11, s12, s8
	s_cmp_gt_i32 s11, -1
	s_mov_b64 s[8:9], -1
	s_cbranch_scc0 .LBB0_1047
	s_lshl_b32 s12, s11, 6
	s_mov_b64 s[8:9], 0
